# attention units visited per XCD row-group in reverse production order (most recently written q/k/v rows first)
# speedup vs baseline: 1.0180x; 1.0180x over previous
.Lprio_a:
	s_load_dwordx2 s[4:5], s[0:1], 0xa8
	v_mov_b32_e32 v187, v240
	s_waitcnt lgkmcnt(0)
	v_mov_b32_e32 v0, s5
	v_mov_b32_e32 v1, s4
	s_nop 0
	v_readfirstlane_b32 s42, v0
	v_mov_b32_e32 v0, s2
	v_readfirstlane_b32 s41, v1
	v_readfirstlane_b32 s33, v0
	v_mov_b32_e32 v0, s24
	s_cmpk_gt_i32 s33, 0x2ff
	v_readfirstlane_b32 s40, v0
	s_cbranch_scc1 .LBB0_572
	s_add_u32 s8, s41, 0x9800000
	s_addc_u32 s9, s42, 0
	s_add_u32 s10, s41, 0x3790000
	s_addc_u32 s11, s42, 0
	s_add_u32 s12, s41, 0xc800000
	s_addc_u32 s13, s42, 0
	s_add_u32 s14, s41, 0xd400000
	s_addc_u32 s15, s42, 0
	s_add_u32 s16, s41, 0x17600000
	s_addc_u32 s17, s42, 0
	s_movk_i32 s43, 0x800
	s_mov_b32 s19, 0
	v_mov_b32_e32 v1, 0
	s_movk_i32 s44, 0x100
	s_movk_i32 s45, 0x90
	s_movk_i32 s46, 0x2400
	s_add_i32 s47, 0, 0x1200
	s_mov_b32 s48, 0xf149f2ca
	s_movk_i32 s49, 0xffe0
	v_mov_b32_e32 v189, 0xf149f2ca
	v_mov_b32_e32 v190, 0x160
	s_lshr_b32 s93, s33, 5
	s_mul_i32 s93, s93, 0x60
	s_and_b32 s50, s33, 31
	s_add_i32 s93, s93, s50
	s_add_i32 s50, s93, 64
	s_branch .LBB0_514
.LBB0_513:
	v_mov_b32_e32 v2, v0
	s_nop 1
	v_permlane32_swap_b32_e32 v0, v2
	v_add_f32_e32 v4, v0, v2
	v_div_scale_f32 v5, s[4:5], v4, v4, 1.0
	v_rcp_f32_e32 v8, v5
	v_lshl_add_u64 v[2:3], v[184:185], 1, s[16:17]
	v_lshlrev_b32_e32 v0, 1, v193
	v_lshl_add_u64 v[6:7], v[2:3], 0, v[0:1]
	v_fma_f32 v0, -v5, v8, 1.0
	v_fmac_f32_e32 v8, v0, v8
	v_div_scale_f32 v0, vcc, 1.0, v4, 1.0
	v_mul_f32_e32 v2, v0, v8
	v_fma_f32 v3, -v5, v2, v0
	v_fmac_f32_e32 v2, v3, v8
	v_fma_f32 v0, -v5, v2, v0
	v_div_fmas_f32 v0, v0, v8, v2
	v_div_fixup_f32 v0, v0, v4, 1.0
	v_lshlrev_b64 v[2:3], 11, v[182:183]
	v_lshl_add_u64 v[8:9], v[6:7], 0, v[2:3]
	v_pk_mul_f32 v[2:3], v[64:65], v[0:1] op_sel_hi:[1,0]
	v_pk_mul_f32 v[4:5], v[66:67], v[0:1] op_sel_hi:[1,0]
	v_cvt_pk_bf16_f32 v2, v2, v3
	v_cvt_pk_bf16_f32 v3, v4, v5
	v_pk_mul_f32 v[4:5], v[68:69], v[0:1] op_sel_hi:[1,0]
	v_pk_mul_f32 v[10:11], v[70:71], v[0:1] op_sel_hi:[1,0]
	v_cvt_pk_bf16_f32 v4, v4, v5
	v_cvt_pk_bf16_f32 v5, v10, v11
	s_nop 0
	v_permlane32_swap_b32_e32 v2, v4
	v_permlane32_swap_b32_e32 v3, v5
	global_store_dwordx4 v[8:9], v[2:5], off
	v_pk_mul_f32 v[10:11], v[78:79], v[0:1] op_sel_hi:[1,0]
	s_sub_i32 s50, s50, 32
	v_pk_mul_f32 v[2:3], v[72:73], v[0:1] op_sel_hi:[1,0]
	v_pk_mul_f32 v[4:5], v[74:75], v[0:1] op_sel_hi:[1,0]
	v_cvt_pk_bf16_f32 v2, v2, v3
	v_cvt_pk_bf16_f32 v3, v4, v5
	v_pk_mul_f32 v[4:5], v[76:77], v[0:1] op_sel_hi:[1,0]
	s_cmp_lt_i32 s50, s93
	v_cvt_pk_bf16_f32 v4, v4, v5
	v_cvt_pk_bf16_f32 v5, v10, v11
	s_nop 0
	v_permlane32_swap_b32_e32 v2, v4
	v_permlane32_swap_b32_e32 v3, v5
	global_store_dwordx4 v[8:9], v[2:5], off offset:32
	v_pk_mul_f32 v[10:11], v[54:55], v[0:1] op_sel_hi:[1,0]
	s_nop 0
	v_pk_mul_f32 v[2:3], v[48:49], v[0:1] op_sel_hi:[1,0]
	v_pk_mul_f32 v[4:5], v[50:51], v[0:1] op_sel_hi:[1,0]
	v_cvt_pk_bf16_f32 v2, v2, v3
	v_cvt_pk_bf16_f32 v3, v4, v5
	v_pk_mul_f32 v[4:5], v[52:53], v[0:1] op_sel_hi:[1,0]
	s_nop 0
	v_cvt_pk_bf16_f32 v4, v4, v5
	v_cvt_pk_bf16_f32 v5, v10, v11
	s_nop 0
	v_permlane32_swap_b32_e32 v2, v4
	v_permlane32_swap_b32_e32 v3, v5
	global_store_dwordx4 v[8:9], v[2:5], off offset:64
	v_pk_mul_f32 v[10:11], v[62:63], v[0:1] op_sel_hi:[1,0]
	s_nop 0
	v_pk_mul_f32 v[2:3], v[56:57], v[0:1] op_sel_hi:[1,0]
	v_pk_mul_f32 v[4:5], v[58:59], v[0:1] op_sel_hi:[1,0]
	v_cvt_pk_bf16_f32 v2, v2, v3
	v_cvt_pk_bf16_f32 v3, v4, v5
	v_pk_mul_f32 v[4:5], v[60:61], v[0:1] op_sel_hi:[1,0]
	v_mov_b32_e32 v0, v192
	s_nop 1
	v_permlane32_swap_b32_e32 v192, v0
	v_add_f32_e32 v0, v192, v0
	v_cvt_pk_bf16_f32 v4, v4, v5
	v_cvt_pk_bf16_f32 v5, v10, v11
	v_div_scale_f32 v10, s[4:5], v0, v0, 1.0
	v_rcp_f32_e32 v11, v10
	v_permlane32_swap_b32_e32 v2, v4
	v_permlane32_swap_b32_e32 v3, v5
	global_store_dwordx4 v[8:9], v[2:5], off offset:96
	s_nop 1
	v_fma_f32 v2, -v10, v11, 1.0
	v_fmac_f32_e32 v11, v2, v11
	v_div_scale_f32 v2, vcc, 1.0, v0, 1.0
	v_mul_f32_e32 v3, v2, v11
	v_fma_f32 v4, -v10, v3, v2
	v_fmac_f32_e32 v3, v4, v11
	v_fma_f32 v2, -v10, v3, v2
	v_div_fmas_f32 v2, v2, v11, v3
	v_div_fixup_f32 v0, v2, v0, 1.0
	v_lshlrev_b64 v[2:3], 11, v[180:181]
	v_lshl_add_u64 v[6:7], v[6:7], 0, v[2:3]
	v_pk_mul_f32 v[2:3], v[32:33], v[0:1] op_sel_hi:[1,0]
	v_pk_mul_f32 v[4:5], v[34:35], v[0:1] op_sel_hi:[1,0]
	v_cvt_pk_bf16_f32 v2, v2, v3
	v_cvt_pk_bf16_f32 v3, v4, v5
	v_pk_mul_f32 v[4:5], v[36:37], v[0:1] op_sel_hi:[1,0]
	v_pk_mul_f32 v[8:9], v[38:39], v[0:1] op_sel_hi:[1,0]
	v_cvt_pk_bf16_f32 v4, v4, v5
	v_cvt_pk_bf16_f32 v5, v8, v9
	s_nop 0
	v_permlane32_swap_b32_e32 v2, v4
	v_permlane32_swap_b32_e32 v3, v5
	global_store_dwordx4 v[6:7], v[2:5], off
	v_pk_mul_f32 v[8:9], v[46:47], v[0:1] op_sel_hi:[1,0]
	s_nop 0
	v_pk_mul_f32 v[2:3], v[40:41], v[0:1] op_sel_hi:[1,0]
	v_pk_mul_f32 v[4:5], v[42:43], v[0:1] op_sel_hi:[1,0]
	v_cvt_pk_bf16_f32 v2, v2, v3
	v_cvt_pk_bf16_f32 v3, v4, v5
	v_pk_mul_f32 v[4:5], v[44:45], v[0:1] op_sel_hi:[1,0]
	s_nop 0
	v_cvt_pk_bf16_f32 v4, v4, v5
	v_cvt_pk_bf16_f32 v5, v8, v9
	s_nop 0
	v_permlane32_swap_b32_e32 v2, v4
	v_permlane32_swap_b32_e32 v3, v5
	global_store_dwordx4 v[6:7], v[2:5], off offset:32
	v_pk_mul_f32 v[8:9], v[22:23], v[0:1] op_sel_hi:[1,0]
	s_nop 0
	v_pk_mul_f32 v[2:3], v[16:17], v[0:1] op_sel_hi:[1,0]
	v_pk_mul_f32 v[4:5], v[18:19], v[0:1] op_sel_hi:[1,0]
	v_cvt_pk_bf16_f32 v2, v2, v3
	v_cvt_pk_bf16_f32 v3, v4, v5
	v_pk_mul_f32 v[4:5], v[20:21], v[0:1] op_sel_hi:[1,0]
	s_nop 0
	v_cvt_pk_bf16_f32 v4, v4, v5
	v_cvt_pk_bf16_f32 v5, v8, v9
	s_nop 0
	v_permlane32_swap_b32_e32 v2, v4
	v_permlane32_swap_b32_e32 v3, v5
	global_store_dwordx4 v[6:7], v[2:5], off offset:64
	v_pk_mul_f32 v[8:9], v[30:31], v[0:1] op_sel_hi:[1,0]
	s_nop 0
	v_pk_mul_f32 v[2:3], v[24:25], v[0:1] op_sel_hi:[1,0]
	v_pk_mul_f32 v[4:5], v[26:27], v[0:1] op_sel_hi:[1,0]
	v_cvt_pk_bf16_f32 v2, v2, v3
	v_cvt_pk_bf16_f32 v3, v4, v5
	v_pk_mul_f32 v[4:5], v[28:29], v[0:1] op_sel_hi:[1,0]
	s_nop 0
	v_cvt_pk_bf16_f32 v4, v4, v5
	v_cvt_pk_bf16_f32 v5, v8, v9
	s_nop 0
	v_permlane32_swap_b32_e32 v2, v4
	v_permlane32_swap_b32_e32 v3, v5
	global_store_dwordx4 v[6:7], v[2:5], off offset:96
	s_waitcnt lgkmcnt(0)
	s_barrier
	s_cbranch_scc1 .LBB0_572
